# speedup vs baseline: 1.0402x; 1.0016x over previous
; __device__ __forceinline__ int v_st(int k, int c) { const int kk = (k & ~0xC) | ((k & 4) << 1) | ((k & 8) >> 1); return ((kk >> 3) * 4 + (c >> 5)) * 512 + ((kk & 7) * 32 + (c & 31)) * 2; }
; __device__ __forceinline__ int v_rd_base(int lane) { return ((lane & 3) << 3) | (((lane >> 2) & 3) << 6) | (((lane >> 4) & 1) << 5) | (((lane >> 5) & 1) << 8); }
; #define SWRITE(b, i) do { *(bf16x8*)((char*)V_lds + (b) * SHM_V + vst) = sr_[i].v; \
;     *(bf16x8*)((char*)K_lds + (b) * SHM_K + ksw0) = sr_[i].k0; \
;     if (k2) *(bf16x8*)((char*)K_lds + (b) * SHM_K + ksw1) = sr_[i].k1; } while (0)
; template <int DQK, bool FIX>
; __device__ __forceinline__ void attn_item(const bf16* Qb, const bf16* __restrict__ Kh, const bf16* __restrict__ Vh,
;                                           u16* Ob, int q0, int L, int NT, char* lds, float mC) {
;     ...
;   int tid = threadIdx.x; asm volatile("" : "+v"(tid));
;   const int wid = tid >> 6, lane = tid & 63, r32 = lane & 31, hi = lane >> 5;
;   bf16* V_lds = (bf16*)lds; bf16* K_lds = (bf16*)(lds + 2 * SHM_V);
;   float* ws = (float*)(lds + 2 * SHM_V + 2 * SHM_K) + wid * 64; float* li_l = ws; float* al_l = ws + 32;
;   float m_reg = -1e30f, l_reg = 0; f32x16 o[2] = {}; bf16x8 qr[ND];
;   __syncthreads();
;   { int qrow = q0 + wid * 32 + r32; if (qrow > L - 1) qrow = L - 1;
;     const bf16* Qw = Qb + (long)qrow * ldq + hi * 8;
; #pragma unroll
;     for (int d0 = 0; d0 < ND; ++d0) qr[d0] = *reinterpret_cast<const bf16x8*>(Qw + d0 * 16); }
;   const int vr = tid >> 3, vc = (tid & 7) * 8, vst = v_st(vr, vc);
;   const int kr0 = tid / KCH, kc0 = (tid % KCH) * 8, kr1 = (tid + 512) / KCH, kc1 = ((tid + 512) % KCH) * 8;
;   const bool k2 = (DQK == 96) && (tid < 256);
;   const int ksw0 = KSWZ(kr0, kc0 * 2), ksw1 = KSWZ(kr1, kc1 * 2);
;   const int vb0 = (int)(uintptr_t)V_lds + v_rd_base(lane);
;   struct { bf16x8 v, k0, k1; } sr_[2];
;     ...
;   f32x16 pA0, pA1, pB0, pB1; float mnA = 0.f, mnB = 0.f, alA = 1.f, alB = 1.f; bf16x8 pa0, pa1, pa2, pa3;
;   constexpr int SE = 0, SO = 1;
;   const bool act = (q0 + wid * 32) < L;
;   SLOAD(SE, 0); asm volatile("s_waitcnt vmcnt(0)" ::: "memory"); SWRITE(0, SE); __syncthreads();
;   if (act) { qkt<DQK>(pA0, pA1, K_lds, qr, r32, hi, 0, L); partialSM<DQK, FIX>(pA0, pA1, m_reg, mnA, alA, mC); }
;   SLOAD(SO, KVBLK); if (2 < NT) SLOAD(SE, 2 * KVBLK);
;   SWAIT(); SWRITE(1, SO); __syncthreads();
.LBB0_829:
	v_writelane_b32 v254, s18, 59
	v_writelane_b32 v255, s16, 0
	v_writelane_b32 v255, s19, 1
	s_or_b64 exec, exec, s[2:3]
	v_lshlrev_b64 v[2:3], 8, v[18:19]
	v_mov_b32_e32 v29, v1
	v_lshl_add_u64 v[2:3], s[14:15], 0, v[2:3]
	v_lshl_add_u64 v[2:3], v[2:3], 0, v[28:29]
	s_movk_i32 s2, 0x4000
	v_add_co_u32_e32 v4, vcc, s2, v2
	v_lshlrev_b64 v[18:19], 1, v[26:27]
	s_nop 0
	v_addc_co_u32_e32 v5, vcc, 0, v3, vcc
	global_load_dwordx4 v[68:71], v[4:5], off
	v_lshlrev_b64 v[4:5], 8, v[22:23]
	v_lshl_add_u64 v[4:5], s[12:13], 0, v[4:5]
	v_lshl_add_u64 v[4:5], v[4:5], 0, v[18:19]
	v_add_co_u32_e32 v6, vcc, s2, v4
	s_mov_b32 s2, 0x8000
	s_nop 0
	v_addc_co_u32_e32 v7, vcc, 0, v5, vcc
	v_add_co_u32_e32 v4, vcc, s2, v4
	global_load_dwordx4 v[26:29], v[6:7], off
	s_nop 0
	v_addc_co_u32_e32 v5, vcc, 0, v5, vcc
	v_add_co_u32_e32 v2, vcc, s2, v2
	global_load_dwordx4 v[118:121], v[4:5], off
	s_nop 0
	v_addc_co_u32_e32 v3, vcc, 0, v3, vcc
	global_load_dwordx4 v[114:117], v[2:3], off
	v_and_b32_e32 v159, 63, v158
	v_lshlrev_b32_e32 v72, 4, v159
	v_lshlrev_b32_e32 v67, 3, v159
	v_lshlrev_b32_e32 v73, 1, v159
	s_cmp_lg_u32 0, -1
	v_lshl_add_u64 v[22:23], v[24:25], 0, s[6:7]
	v_and_b32_e32 v24, 7, v158
	v_and_b32_e32 v72, 0xc0, v72
	v_readlane_b32 s12, v254, 35
	v_lshl_add_u64 v[20:21], v[20:21], 0, s[6:7]
	v_mov_b32_e32 v25, v1
	v_and_b32_e32 v73, 32, v73
	v_and_b32_e32 v74, 0x100, v67
	s_cselect_b32 s2, 0, 0
	v_lshl_add_u64 v[18:19], v[22:23], 0, v[18:19]
	v_lshlrev_b32_e32 v24, 4, v24
	v_and_or_b32 v22, v67, 24, v72
	v_readlane_b32 s13, v254, 36
	v_add_u32_e32 v66, 0, v66
	v_add_u32_e32 v31, 0, v31
	v_add_u32_e32 v32, 0, v32
	v_add_u32_e32 v33, 0, v33
	v_mov_b32_e32 v16, v1
	v_mov_b32_e32 v17, v1
	s_add_i32 s3, s2, 0x4000
	v_readlane_b32 s14, v254, 37
	v_readlane_b32 s15, v254, 38
	v_lshl_add_u64 v[146:147], s[12:13], 0, v[18:19]
	v_lshl_add_u64 v[18:19], v[20:21], 0, v[24:25]
	v_or3_b32 v20, v22, v73, v74
	s_waitcnt vmcnt(2)
	v_mov_b32_e32 v2, v1
	v_mov_b32_e32 v3, v1
	v_mov_b32_e32 v4, v1
	v_mov_b32_e32 v5, v1
	v_mov_b32_e32 v6, v1
	v_mov_b32_e32 v7, v1
	v_mov_b32_e32 v8, v1
	v_mov_b32_e32 v9, v1
	v_mov_b32_e32 v10, v1
	v_mov_b32_e32 v11, v1
	v_mov_b32_e32 v12, v1
	v_mov_b32_e32 v13, v1
	v_mov_b32_e32 v14, v1
	v_mov_b32_e32 v15, v1
	v_add_u32_e32 v167, v66, v30
	v_add_u32_e32 v168, v31, v30
	v_add_u32_e32 v169, v32, v30
	v_lshl_add_u64 v[148:149], s[14:15], 0, v[18:19]
	v_add_u32_e32 v166, s2, v20
	v_add_u32_e32 v170, s3, v20
	v_add_u32_e32 v171, v33, v30
	v_mov_b64_e32 v[96:97], v[16:17]
	s_mov_b32 s73, 4
	s_mov_b32 s78, 0
	v_lshlrev_b32_e32 v162, 2, v155
	v_mov_b32_e32 v163, 0
	s_sub_i32 s79, s96, 64
	s_sub_i32 s72, s96, 32
	s_waitcnt vmcnt(3)
	ds_write_b128 v160, v[68:71] offset:16384
	s_waitcnt vmcnt(2)
	ds_write_b128 v161, v[26:29] offset:49152
	v_mov_b64_e32 v[32:33], v[16:17]
	v_mov_b64_e32 v[80:81], v[16:17]
	v_mov_b64_e32 v[30:31], v[14:15]
	v_mov_b64_e32 v[28:29], v[12:13]
	v_mov_b64_e32 v[26:27], v[10:11]
	v_mov_b64_e32 v[24:25], v[8:9]
	v_mov_b64_e32 v[22:23], v[6:7]
	v_mov_b64_e32 v[20:21], v[4:5]
	v_mov_b64_e32 v[18:19], v[2:3]
	v_mov_b64_e32 v[78:79], v[14:15]
	v_mov_b64_e32 v[76:77], v[12:13]
	v_mov_b64_e32 v[74:75], v[10:11]
	v_mov_b64_e32 v[72:73], v[8:9]
	v_mov_b64_e32 v[70:71], v[6:7]
	v_mov_b64_e32 v[68:69], v[4:5]
	v_mov_b64_e32 v[66:67], v[2:3]
	v_mov_b64_e32 v[94:95], v[14:15]
	v_mov_b64_e32 v[92:93], v[12:13]
	v_mov_b64_e32 v[90:91], v[10:11]
	v_mov_b64_e32 v[88:89], v[8:9]
	v_mov_b64_e32 v[86:87], v[6:7]
	v_mov_b64_e32 v[84:85], v[4:5]
	v_mov_b64_e32 v[82:83], v[2:3]
	s_waitcnt lgkmcnt(0)
	s_barrier
	v_mov_b32_e32 v202, 0
	s_branch .LBB0_832

; #define SBAR() __builtin_amdgcn_sched_barrier(0)
; #define SLOAD(i, key0) do { sr_[i].v = *reinterpret_cast<const bf16x8*>(&Vh[(long)((key0) + vr) * ldv + vc]); \
;     sr_[i].k0 = *reinterpret_cast<const bf16x8*>(&Kh[(long)((key0) + kr0) * ldk + kc0]); \
;     if (k2) sr_[i].k1 = *reinterpret_cast<const bf16x8*>(&Kh[(long)((key0) + kr1) * ldk + kc1]); } while (0)
; __device__ __forceinline__ void finishSM(f32x16& p0, f32x16& p1, float alpha, float& l_reg, bf16x8& pa0, bf16x8& pa1, bf16x8& pa2, bf16x8& pa3) {
; #pragma unroll
;   for (int r = 0; r < 16; ++r) p1[r] = __builtin_amdgcn_exp2f(p1[r]);
;   float ps = 0;
; #pragma unroll
;   for (int r = 0; r < 16; ++r) ps += p0[r];
; #pragma unroll
;   for (int r = 0; r < 16; ++r) ps += p1[r];
;   { auto rr = __builtin_amdgcn_permlane32_swap(__float_as_uint(ps), __float_as_uint(ps), false, false);
;     ps = __uint_as_float(rr[0]) + __uint_as_float(rr[1]); }
;   l_reg = l_reg * alpha + ps;
;     ...
;   PK4(p0, 0, pa0); PK4(p0, 8, pa1); PK4(p1, 0, pa2); PK4(p1, 8, pa3);
;     ...
; }
; template <int DQK>
; __device__ __forceinline__ void qkt(f32x16& p0, f32x16& p1, const bf16* Ks, const bf16x8* qr, int r32, int hi, int k0, int L) {
;   p0 = f32x16{}; p1 = f32x16{};
; #pragma unroll
;   for (int d0 = 0; d0 < DQK / 16; ++d0) { int cb = (d0 * 16 + hi * 8) * 2;
;     bf16x8 b0 = *reinterpret_cast<const bf16x8*>((const char*)Ks + KSWZ(r32, cb));
;     bf16x8 b1 = *reinterpret_cast<const bf16x8*>((const char*)Ks + KSWZ(32 + r32, cb));
;     p0 = __builtin_amdgcn_mfma_f32_32x32x16_bf16(b0, qr[d0], p0, 0, 0, 0);
;     p1 = __builtin_amdgcn_mfma_f32_32x32x16_bf16(b1, qr[d0], p1, 0, 0, 0); }
; template <int DQK, bool FIX>
; __device__ __forceinline__ void attn_item(const bf16* Qb, const bf16* __restrict__ Kh, const bf16* __restrict__ Vh,
;                                           u16* Ob, int q0, int L, int NT, char* lds, float mC) {
;     ...
;   for (int j = 1; j + 1 < NT; j += 2) {
;     if (act) { SBAR(); qkt<DQK>(pB0, pB1, (bf16*)((char*)K_lds + SHM_K), qr, r32, hi, j * KVBLK, L);
;       finishSM(pA0, pA1, alA, l_reg, pa0, pa1, pa2, pa3); SBAR(); }
;     SLOAD(SO, (j + 2) * KVBLK); SBAR();
;     if (act) { pv_d0(o, vb0, pa0, pa1, pa2, pa3); partialSM<DQK, FIX>(pB0, pB1, m_reg, mnB, alB, mC); }
.LBB0_832:
	s_and_saveexec_b64 s[2:3], s[8:9]
	s_cbranch_execz .LBB0_838
	s_add_i32 s6, s78, 64
	s_cmp_le_u32 s6, s79
	s_cbranch_scc0 .Lslow64a
	s_and_b64 vcc, exec, s[10:11]
	s_cbranch_vccz .Lslow64a
	ds_read_b128 v[222:225], v167 offset:49152
	ds_read_b128 v[226:229], v168 offset:49152
	ds_read_b128 v[230:233], v167 offset:57344
	ds_read_b128 v[234:237], v168 offset:57344
	ds_read_b128 v[238:241], v169 offset:49152
	ds_read_b128 v[242:245], v169 offset:57344
	ds_read_b128 v[246:249], v171 offset:49152
	ds_read_b128 v[250:253], v171 offset:57344
	v_cvt_pk_bf16_f32 v130, v50, v51
	v_cvt_pk_bf16_f32 v131, v52, v53
	v_cvt_pk_bf16_f32 v132, v54, v55
	v_cvt_pk_bf16_f32 v133, v56, v57
	v_cvt_pk_bf16_f32 v134, v58, v59
	v_cvt_pk_bf16_f32 v135, v60, v61
	v_cvt_pk_bf16_f32 v136, v62, v63
	v_cvt_pk_bf16_f32 v137, v64, v65
	s_waitcnt lgkmcnt(7)
	v_mfma_f32_32x32x16_bf16 v[66:81], v[222:225], v[98:101], 0
	ds_read_b64_tr_b16 v[186:187], v166 offset:0
	ds_read_b64_tr_b16 v[188:189], v166 offset:2048
	ds_read_b64_tr_b16 v[190:191], v166 offset:4096
	ds_read_b64_tr_b16 v[192:193], v166 offset:6144
	v_exp_f32_e32 v34, v34
	v_exp_f32_e32 v35, v35
	v_exp_f32_e32 v36, v36
	s_waitcnt lgkmcnt(10)
	v_mfma_f32_32x32x16_bf16 v[66:81], v[226:229], v[102:105], v[66:81]
	ds_read_b64_tr_b16 v[194:195], v166 offset:8192
	ds_read_b64_tr_b16 v[196:197], v166 offset:10240
	ds_read_b64_tr_b16 v[198:199], v166 offset:12288
	ds_read_b64_tr_b16 v[200:201], v166 offset:14336
	v_exp_f32_e32 v37, v37
	v_exp_f32_e32 v38, v38
	v_exp_f32_e32 v39, v39
	s_waitcnt lgkmcnt(13)
	v_mfma_f32_32x32x16_bf16 v[82:97], v[230:233], v[98:101], 0
	v_exp_f32_e32 v40, v40
	v_exp_f32_e32 v41, v41
	v_exp_f32_e32 v42, v42
	s_waitcnt lgkmcnt(12)
	v_mfma_f32_32x32x16_bf16 v[82:97], v[234:237], v[102:105], v[82:97]
	v_exp_f32_e32 v43, v43
	v_exp_f32_e32 v44, v44
	v_exp_f32_e32 v45, v45
	s_waitcnt lgkmcnt(11)
	v_mfma_f32_32x32x16_bf16 v[66:81], v[238:241], v[106:109], v[66:81]
	v_exp_f32_e32 v46, v46
	v_exp_f32_e32 v47, v47
	v_exp_f32_e32 v48, v48
	s_waitcnt lgkmcnt(10)
	v_mfma_f32_32x32x16_bf16 v[82:97], v[242:245], v[106:109], v[82:97]
	ds_read_b64_tr_b16 v[222:223], v166 offset:512
	ds_read_b64_tr_b16 v[224:225], v166 offset:2560
	ds_read_b64_tr_b16 v[226:227], v166 offset:4608
	ds_read_b64_tr_b16 v[228:229], v166 offset:6656
	v_exp_f32_e32 v49, v49
	v_cvt_pk_bf16_f32 v138, v34, v35
	v_cvt_pk_bf16_f32 v139, v36, v37
	v_cvt_pk_bf16_f32 v140, v38, v39
	s_waitcnt lgkmcnt(13)
	v_mfma_f32_32x32x16_bf16 v[66:81], v[246:249], v[110:113], v[66:81]
	v_cvt_pk_bf16_f32 v141, v40, v41
	v_cvt_pk_bf16_f32 v142, v42, v43
	v_cvt_pk_bf16_f32 v143, v44, v45
	v_cvt_pk_bf16_f32 v144, v46, v47
	s_waitcnt lgkmcnt(12)
	v_mfma_f32_32x32x16_bf16 v[82:97], v[250:253], v[110:113], v[82:97]
	ds_read_b64_tr_b16 v[230:231], v166 offset:8704
	ds_read_b64_tr_b16 v[232:233], v166 offset:10752
	ds_read_b64_tr_b16 v[234:235], v166 offset:12800
	s_waitcnt lgkmcnt(14)
	ds_read_b64_tr_b16 v[236:237], v166 offset:14848
	v_cvt_pk_bf16_f32 v145, v48, v49
	s_or_b64 exec, exec, s[2:3]
	v_lshl_add_u64 v[152:153], v[148:149], 0, s[4:5]
	v_add_co_u32_e32 v122, vcc, 0x2ced0000, v152
	v_lshl_add_u64 v[150:151], v[146:147], 0, s[4:5]
	s_nop 0
	v_addc_co_u32_e32 v123, vcc, 0, v153, vcc
	v_add_co_u32_e32 v126, vcc, 0x119cc000, v150
	global_load_dwordx4 v[122:125], v[122:123], off offset:2048
	s_nop 0
	v_addc_co_u32_e32 v127, vcc, 0, v151, vcc
	global_load_dwordx4 v[126:129], v[126:127], off
	s_and_saveexec_b64 s[2:3], s[8:9]
	s_waitcnt lgkmcnt(14)
	v_mfma_f32_32x32x16_bf16 v[2:17], v[130:133], v[186:189], v[2:17]
	v_add_f32_e32 v252, 0, v50
	v_add_f32_e32 v252, v51, v252
	v_add_f32_e32 v252, v52, v252
	v_add_f32_e32 v252, v53, v252
	v_exp_f32_e32 v66, v66
	v_exp_f32_e32 v67, v67
	s_waitcnt lgkmcnt(12)
	v_mfma_f32_32x32x16_bf16 v[2:17], v[134:137], v[190:193], v[2:17]
	v_add_f32_e32 v252, v54, v252
	v_add_f32_e32 v252, v55, v252
	v_add_f32_e32 v252, v56, v252
	v_add_f32_e32 v252, v57, v252
	v_exp_f32_e32 v68, v68
	v_exp_f32_e32 v69, v69
	s_waitcnt lgkmcnt(10)
	v_mfma_f32_32x32x16_bf16 v[2:17], v[138:141], v[194:197], v[2:17]
	v_add_f32_e32 v252, v58, v252
	v_add_f32_e32 v252, v59, v252
	v_add_f32_e32 v252, v60, v252
	v_add_f32_e32 v252, v61, v252
	v_exp_f32_e32 v70, v70
	v_exp_f32_e32 v71, v71
	s_waitcnt lgkmcnt(8)
	v_mfma_f32_32x32x16_bf16 v[2:17], v[142:145], v[198:201], v[2:17]
	v_add_f32_e32 v252, v62, v252
	v_add_f32_e32 v252, v63, v252
	v_add_f32_e32 v252, v64, v252
	v_add_f32_e32 v252, v65, v252
	v_exp_f32_e32 v72, v72
	v_exp_f32_e32 v73, v73
	s_waitcnt lgkmcnt(6)
	v_mfma_f32_32x32x16_bf16 v[18:33], v[130:133], v[222:225], v[18:33]
	v_add_f32_e32 v252, v34, v252
	v_add_f32_e32 v252, v35, v252
	v_add_f32_e32 v252, v36, v252
	v_add_f32_e32 v252, v37, v252
	v_exp_f32_e32 v74, v74
	v_exp_f32_e32 v75, v75
	s_waitcnt lgkmcnt(4)
	v_mfma_f32_32x32x16_bf16 v[18:33], v[134:137], v[226:229], v[18:33]
	v_add_f32_e32 v252, v38, v252
	v_add_f32_e32 v252, v39, v252
	v_add_f32_e32 v252, v40, v252
	v_add_f32_e32 v252, v41, v252
	v_exp_f32_e32 v76, v76
	v_exp_f32_e32 v77, v77
	s_waitcnt lgkmcnt(2)
	v_mfma_f32_32x32x16_bf16 v[18:33], v[138:141], v[230:233], v[18:33]
	v_add_f32_e32 v252, v42, v252
	v_add_f32_e32 v252, v43, v252
	v_add_f32_e32 v252, v44, v252
	v_add_f32_e32 v252, v45, v252
	v_exp_f32_e32 v78, v78
	v_exp_f32_e32 v79, v79
	s_waitcnt lgkmcnt(0)
	v_mfma_f32_32x32x16_bf16 v[18:33], v[142:145], v[234:237], v[18:33]
	v_add_f32_e32 v252, v46, v252
	v_add_f32_e32 v252, v47, v252
	v_add_f32_e32 v252, v48, v252
	v_add_f32_e32 v252, v49, v252
	v_exp_f32_e32 v80, v80
	v_exp_f32_e32 v81, v81
	v_add_f32_e32 v202, v202, v252
	s_branch .LBB0_842

; #define SBAR() __builtin_amdgcn_sched_barrier(0)
; #define SLOAD(i, key0) do { sr_[i].v = *reinterpret_cast<const bf16x8*>(&Vh[(long)((key0) + vr) * ldv + vc]); \
;     sr_[i].k0 = *reinterpret_cast<const bf16x8*>(&Kh[(long)((key0) + kr0) * ldk + kc0]); \
;     if (k2) sr_[i].k1 = *reinterpret_cast<const bf16x8*>(&Kh[(long)((key0) + kr1) * ldk + kc1]); } while (0)
; template <int D0> __device__ __forceinline__ void pv_one(f32x16& od, int vb, bf16x8 pa0, bf16x8 pa1, bf16x8 pa2, bf16x8 pa3) {
;   const s16x4 l0 = tr_read<v_rd_off(D0, 0, 0)>(vb), h0 = tr_read<v_rd_off(D0, 0, 1)>(vb), l1 = tr_read<v_rd_off(D0, 1, 0)>(vb), h1 = tr_read<v_rd_off(D0, 1, 1)>(vb);
;   const s16x4 l2 = tr_read<v_rd_off(D0, 2, 0)>(vb), h2 = tr_read<v_rd_off(D0, 2, 1)>(vb), l3 = tr_read<v_rd_off(D0, 3, 0)>(vb), h3 = tr_read<v_rd_off(D0, 3, 1)>(vb);
;   asm volatile("s_waitcnt lgkmcnt(0)" ::: "memory"); SBAR();
;     ...
;   od = __builtin_amdgcn_mfma_f32_32x32x16_bf16(pa0, PK(l0, h0), od, 0, 0, 0);
;   od = __builtin_amdgcn_mfma_f32_32x32x16_bf16(pa1, PK(l1, h1), od, 0, 0, 0);
;   od = __builtin_amdgcn_mfma_f32_32x32x16_bf16(pa2, PK(l2, h2), od, 0, 0, 0);
;   od = __builtin_amdgcn_mfma_f32_32x32x16_bf16(pa3, PK(l3, h3), od, 0, 0, 0);
;     ...
; }
; __device__ __forceinline__ void pv_d0(f32x16* o, int vb, bf16x8 pa0, bf16x8 pa1, bf16x8 pa2, bf16x8 pa3) {
;   pv_one<0>(o[0], vb, pa0, pa1, pa2, pa3); pv_one<1>(o[1], vb, pa0, pa1, pa2, pa3);
; }
; template <int DQK, bool FIX>
; __device__ __forceinline__ void attn_item(const bf16* Qb, const bf16* __restrict__ Kh, const bf16* __restrict__ Vh,
;                                           u16* Ob, int q0, int L, int NT, char* lds, float mC) {
;     ...
;     if (act) { SBAR(); qkt<DQK>(pA0, pA1, K_lds, qr, r32, hi, (j + 1) * KVBLK, L);
;       finishSM(pB0, pB1, alB, l_reg, pa0, pa1, pa2, pa3); SBAR(); }
;     if (j + 3 < NT) SLOAD(SE, (j + 3) * KVBLK); SBAR();
;     if (act) { pv_d0(o, vb0 + (int)SHM_V, pa0, pa1, pa2, pa3); partialSM<DQK, FIX>(pA0, pA1, m_reg, mnA, alA, mC); }
.Lfast64b_nl:
	s_and_saveexec_b64 s[6:7], s[8:9]
	s_waitcnt lgkmcnt(14)
	v_mfma_f32_32x32x16_bf16 v[2:17], v[130:133], v[186:189], v[2:17]
	v_add_f32_e32 v252, 0, v66
	v_add_f32_e32 v252, v67, v252
	v_add_f32_e32 v252, v68, v252
	v_add_f32_e32 v252, v69, v252
	v_exp_f32_e32 v50, v50
	v_exp_f32_e32 v51, v51
	s_waitcnt lgkmcnt(12)
	v_mfma_f32_32x32x16_bf16 v[2:17], v[134:137], v[190:193], v[2:17]
	v_add_f32_e32 v252, v70, v252
	v_add_f32_e32 v252, v71, v252
	v_add_f32_e32 v252, v72, v252
	v_add_f32_e32 v252, v73, v252
	v_exp_f32_e32 v52, v52
	v_exp_f32_e32 v53, v53
	s_waitcnt lgkmcnt(10)
	v_mfma_f32_32x32x16_bf16 v[2:17], v[138:141], v[194:197], v[2:17]
	v_add_f32_e32 v252, v74, v252
	v_add_f32_e32 v252, v75, v252
	v_add_f32_e32 v252, v76, v252
	v_add_f32_e32 v252, v77, v252
	v_exp_f32_e32 v54, v54
	v_exp_f32_e32 v55, v55
	s_waitcnt lgkmcnt(8)
	v_mfma_f32_32x32x16_bf16 v[2:17], v[142:145], v[198:201], v[2:17]
	v_add_f32_e32 v252, v78, v252
	v_add_f32_e32 v252, v79, v252
	v_add_f32_e32 v252, v80, v252
	v_add_f32_e32 v252, v81, v252
	v_exp_f32_e32 v56, v56
	v_exp_f32_e32 v57, v57
	s_waitcnt lgkmcnt(6)
	v_mfma_f32_32x32x16_bf16 v[18:33], v[130:133], v[222:225], v[18:33]
	v_add_f32_e32 v252, v82, v252
	v_add_f32_e32 v252, v83, v252
	v_add_f32_e32 v252, v84, v252
	v_add_f32_e32 v252, v85, v252
	v_exp_f32_e32 v58, v58
	v_exp_f32_e32 v59, v59
	s_waitcnt lgkmcnt(4)
	v_mfma_f32_32x32x16_bf16 v[18:33], v[134:137], v[226:229], v[18:33]
	v_add_f32_e32 v252, v86, v252
	v_add_f32_e32 v252, v87, v252
	v_add_f32_e32 v252, v88, v252
	v_add_f32_e32 v252, v89, v252
	v_exp_f32_e32 v60, v60
	v_exp_f32_e32 v61, v61
	s_waitcnt lgkmcnt(2)
	v_mfma_f32_32x32x16_bf16 v[18:33], v[138:141], v[230:233], v[18:33]
	v_add_f32_e32 v252, v90, v252
	v_add_f32_e32 v252, v91, v252
	v_add_f32_e32 v252, v92, v252
	v_add_f32_e32 v252, v93, v252
	v_exp_f32_e32 v62, v62
	v_exp_f32_e32 v63, v63
	s_waitcnt lgkmcnt(0)
	v_mfma_f32_32x32x16_bf16 v[18:33], v[142:145], v[234:237], v[18:33]
	v_add_f32_e32 v252, v94, v252
	v_add_f32_e32 v252, v95, v252
	v_add_f32_e32 v252, v96, v252
	v_add_f32_e32 v252, v97, v252
	v_exp_f32_e32 v64, v64
	v_exp_f32_e32 v65, v65
	v_add_f32_e32 v202, v202, v252
	s_branch .LBB0_831

; __device__ __forceinline__ void finishSM(f32x16& p0, f32x16& p1, float alpha, float& l_reg, bf16x8& pa0, bf16x8& pa1, bf16x8& pa2, bf16x8& pa3) {
; #pragma unroll
;   for (int r = 0; r < 16; ++r) p1[r] = __builtin_amdgcn_exp2f(p1[r]);
;   float ps = 0;
; #pragma unroll
;   for (int r = 0; r < 16; ++r) ps += p0[r];
; #pragma unroll
;   for (int r = 0; r < 16; ++r) ps += p1[r];
;   { auto rr = __builtin_amdgcn_permlane32_swap(__float_as_uint(ps), __float_as_uint(ps), false, false);
;     ps = __uint_as_float(rr[0]) + __uint_as_float(rr[1]); }
;   l_reg = l_reg * alpha + ps;
;     ...
;   PK4(p0, 0, pa0); PK4(p0, 8, pa1); PK4(p1, 0, pa2); PK4(p1, 8, pa3);
;     ...
; }
; template <int DQK>
; __device__ __forceinline__ void qkt(f32x16& p0, f32x16& p1, const bf16* Ks, const bf16x8* qr, int r32, int hi, int k0, int L) {
;   p0 = f32x16{}; p1 = f32x16{};
; #pragma unroll
;   for (int d0 = 0; d0 < DQK / 16; ++d0) { int cb = (d0 * 16 + hi * 8) * 2;
;     bf16x8 b0 = *reinterpret_cast<const bf16x8*>((const char*)Ks + KSWZ(r32, cb));
;     bf16x8 b1 = *reinterpret_cast<const bf16x8*>((const char*)Ks + KSWZ(32 + r32, cb));
;     p0 = __builtin_amdgcn_mfma_f32_32x32x16_bf16(b0, qr[d0], p0, 0, 0, 0);
;     p1 = __builtin_amdgcn_mfma_f32_32x32x16_bf16(b1, qr[d0], p1, 0, 0, 0); }
;   if (k0 + KVBLK > L) {
; #pragma unroll
;     for (int r = 0; r < 16; ++r) { const int key = k0 + crow(r, hi);
;       if (key >= L) p0[r] = -1e30f;
;       if (key + 32 >= L) p1[r] = -1e30f; }
;   }
; }
; __device__ __forceinline__ int v_st(int k, int c) { const int kk = (k & ~0xC) | ((k & 4) << 1) | ((k & 8) >> 1); return ((kk >> 3) * 4 + (c >> 5)) * 512 + ((kk & 7) * 32 + (c & 31)) * 2; }
; __device__ __forceinline__ int v_rd_base(int lane) { return ((lane & 3) << 3) | (((lane >> 2) & 3) << 6) | (((lane >> 4) & 1) << 5) | (((lane >> 5) & 1) << 8); }
; template <int OFF> __device__ __forceinline__ s16x4 tr_read(int vb) {
;   s16x4 r; asm volatile("ds_read_b64_tr_b16 %0, %1 offset:%2" : "=&v"(r) : "v"(vb), "i"(OFF) : "memory"); return r;
; }
; template <int D0> __device__ __forceinline__ void pv_one(f32x16& od, int vb, bf16x8 pa0, bf16x8 pa1, bf16x8 pa2, bf16x8 pa3) {
;   const s16x4 l0 = tr_read<v_rd_off(D0, 0, 0)>(vb), h0 = tr_read<v_rd_off(D0, 0, 1)>(vb), l1 = tr_read<v_rd_off(D0, 1, 0)>(vb), h1 = tr_read<v_rd_off(D0, 1, 1)>(vb);
.LBB0_853:
	s_and_saveexec_b64 s[2:3], s[8:9]
	v_readlane_b32 s6, v254, 61
	s_cbranch_execz .LBB0_855
	v_mov_b32_e32 v203, v202
	s_nop 1
	v_permlane32_swap_b32_e32 v202, v203
	v_add_f32_e32 v202, v202, v203
	v_add_f32_e32 v163, v163, v202
	v_exp_f32_e32 v66, v34
	v_add_f32_e32 v34, 0, v50
	v_add_f32_e32 v34, v51, v34
	v_add_f32_e32 v34, v52, v34
	v_add_f32_e32 v34, v53, v34
	v_add_f32_e32 v34, v54, v34
	v_add_f32_e32 v34, v55, v34
	v_add_f32_e32 v34, v56, v34
	v_add_f32_e32 v34, v57, v34
	v_add_f32_e32 v34, v58, v34
	v_add_f32_e32 v34, v59, v34
	v_add_f32_e32 v34, v60, v34
	v_add_f32_e32 v34, v61, v34
	v_add_f32_e32 v34, v62, v34
	v_exp_f32_e32 v67, v35
	v_add_f32_e32 v34, v63, v34
	v_exp_f32_e32 v68, v36
	v_add_f32_e32 v34, v64, v34
	v_exp_f32_e32 v69, v37
	v_add_f32_e32 v34, v65, v34
	v_exp_f32_e32 v70, v38
	v_add_f32_e32 v34, v66, v34
	v_exp_f32_e32 v71, v39
	v_add_f32_e32 v34, v67, v34
	v_exp_f32_e32 v72, v40
	v_add_f32_e32 v34, v68, v34
	v_exp_f32_e32 v73, v41
	v_add_f32_e32 v34, v69, v34
	v_exp_f32_e32 v74, v42
	v_add_f32_e32 v34, v70, v34
	v_exp_f32_e32 v75, v43
	v_add_f32_e32 v34, v71, v34
	v_exp_f32_e32 v76, v44
	v_add_f32_e32 v34, v72, v34
	v_exp_f32_e32 v77, v45
	v_add_f32_e32 v34, v73, v34
	v_exp_f32_e32 v78, v46
	v_add_f32_e32 v34, v74, v34
	v_exp_f32_e32 v79, v47
	v_add_f32_e32 v34, v75, v34
	v_exp_f32_e32 v80, v48
	v_add_f32_e32 v34, v76, v34
	v_exp_f32_e32 v49, v49
	v_add_f32_e32 v34, v77, v34
	v_add_f32_e32 v34, v78, v34
	v_add_f32_e32 v34, v79, v34
	v_add_f32_e32 v34, v80, v34
	v_add_f32_e32 v34, v49, v34
	v_mov_b32_e32 v35, v34
	s_nop 1
	v_permlane32_swap_b32_e32 v34, v35
	v_add_f32_e32 v34, v34, v35
	v_add_f32_e32 v163, v163, v34
	v_cvt_pk_bf16_f32 v34, v50, v51
	v_cvt_pk_bf16_f32 v35, v52, v53
	v_cvt_pk_bf16_f32 v36, v54, v55
	v_cvt_pk_bf16_f32 v37, v56, v57
	v_cvt_pk_bf16_f32 v38, v58, v59
	v_cvt_pk_bf16_f32 v39, v60, v61
	v_cvt_pk_bf16_f32 v40, v62, v63
	v_cvt_pk_bf16_f32 v41, v64, v65
	v_cvt_pk_bf16_f32 v42, v66, v67
	v_cvt_pk_bf16_f32 v43, v68, v69
	v_cvt_pk_bf16_f32 v44, v70, v71
	v_cvt_pk_bf16_f32 v45, v72, v73
	v_cvt_pk_bf16_f32 v46, v74, v75
	v_cvt_pk_bf16_f32 v47, v76, v77
	v_cvt_pk_bf16_f32 v48, v78, v79
	v_cvt_pk_bf16_f32 v49, v80, v49
	ds_read_b64_tr_b16 v[50:51], v166 offset:0
	ds_read_b64_tr_b16 v[52:53], v166 offset:0x800
	ds_read_b64_tr_b16 v[54:55], v166 offset:0x1000
	ds_read_b64_tr_b16 v[56:57], v166 offset:0x1800
	ds_read_b64_tr_b16 v[58:59], v166 offset:0x2000
	ds_read_b64_tr_b16 v[60:61], v166 offset:0x2800
	ds_read_b64_tr_b16 v[62:63], v166 offset:0x3000
	ds_read_b64_tr_b16 v[64:65], v166 offset:0x3800
	s_waitcnt lgkmcnt(0)
	s_nop 0
	v_mfma_f32_32x32x16_bf16 v[2:17], v[34:37], v[50:53], v[2:17]
	ds_read_b64_tr_b16 v[50:51], v166 offset:0x200
	ds_read_b64_tr_b16 v[52:53], v166 offset:0xa00
	v_mfma_f32_32x32x16_bf16 v[2:17], v[38:41], v[54:57], v[2:17]
	ds_read_b64_tr_b16 v[54:55], v166 offset:0x1200
	ds_read_b64_tr_b16 v[56:57], v166 offset:0x1a00
	v_mfma_f32_32x32x16_bf16 v[2:17], v[42:45], v[58:61], v[2:17]
	ds_read_b64_tr_b16 v[58:59], v166 offset:0x2200
	ds_read_b64_tr_b16 v[60:61], v166 offset:0x2a00
	v_mfma_f32_32x32x16_bf16 v[2:17], v[46:49], v[62:65], v[2:17]
	ds_read_b64_tr_b16 v[62:63], v166 offset:0x3200
	ds_read_b64_tr_b16 v[64:65], v166 offset:0x3a00
	s_waitcnt lgkmcnt(0)
	v_mfma_f32_32x32x16_bf16 v[18:33], v[34:37], v[50:53], v[18:33]
	v_mfma_f32_32x32x16_bf16 v[18:33], v[38:41], v[54:57], v[18:33]
	v_mfma_f32_32x32x16_bf16 v[18:33], v[42:45], v[58:61], v[18:33]
	v_mfma_f32_32x32x16_bf16 v[18:33], v[46:49], v[62:65], v[18:33]

; __device__ __forceinline__ int v_st(int k, int c) { const int kk = (k & ~0xC) | ((k & 4) << 1) | ((k & 8) >> 1); return ((kk >> 3) * 4 + (c >> 5)) * 512 + ((kk & 7) * 32 + (c & 31)) * 2; }
; __device__ __forceinline__ int v_rd_base(int lane) { return ((lane & 3) << 3) | (((lane >> 2) & 3) << 6) | (((lane >> 4) & 1) << 5) | (((lane >> 5) & 1) << 8); }
; #define SWRITE(b, i) do { *(bf16x8*)((char*)V_lds + (b) * SHM_V + vst) = sr_[i].v; \
;     *(bf16x8*)((char*)K_lds + (b) * SHM_K + ksw0) = sr_[i].k0; \
;     if (k2) *(bf16x8*)((char*)K_lds + (b) * SHM_K + ksw1) = sr_[i].k1; } while (0)
; template <int DQK, bool FIX>
; __device__ __forceinline__ void attn_item(const bf16* Qb, const bf16* __restrict__ Kh, const bf16* __restrict__ Vh,
;                                           u16* Ob, int q0, int L, int NT, char* lds, float mC) {
;     ...
;   int tid = threadIdx.x; asm volatile("" : "+v"(tid));
;   const int wid = tid >> 6, lane = tid & 63, r32 = lane & 31, hi = lane >> 5;
;   bf16* V_lds = (bf16*)lds; bf16* K_lds = (bf16*)(lds + 2 * SHM_V);
;   float* ws = (float*)(lds + 2 * SHM_V + 2 * SHM_K) + wid * 64; float* li_l = ws; float* al_l = ws + 32;
;   float m_reg = -1e30f, l_reg = 0; f32x16 o[2] = {}; bf16x8 qr[ND];
;   __syncthreads();
;   { int qrow = q0 + wid * 32 + r32; if (qrow > L - 1) qrow = L - 1;
;     const bf16* Qw = Qb + (long)qrow * ldq + hi * 8;
; #pragma unroll
;     for (int d0 = 0; d0 < ND; ++d0) qr[d0] = *reinterpret_cast<const bf16x8*>(Qw + d0 * 16); }
;   const int vr = tid >> 3, vc = (tid & 7) * 8, vst = v_st(vr, vc);
;   const int kr0 = tid / KCH, kc0 = (tid % KCH) * 8, kr1 = (tid + 512) / KCH, kc1 = ((tid + 512) % KCH) * 8;
;   const bool k2 = (DQK == 96) && (tid < 256);
;   const int ksw0 = KSWZ(kr0, kc0 * 2), ksw1 = KSWZ(kr1, kc1 * 2);
;   const int vb0 = (int)(uintptr_t)V_lds + v_rd_base(lane);
;   struct { bf16x8 v, k0, k1; } sr_[2];
;     ...
;   f32x16 pA0, pA1, pB0, pB1; float mnA = 0.f, mnB = 0.f, alA = 1.f, alB = 1.f; bf16x8 pa0, pa1, pa2, pa3;
;   constexpr int SE = 0, SO = 1;
;   const bool act = (q0 + wid * 32) < L;
;   SLOAD(SE, 0); asm volatile("s_waitcnt vmcnt(0)" ::: "memory"); SWRITE(0, SE); __syncthreads();
;   if (act) { qkt<DQK>(pA0, pA1, K_lds, qr, r32, hi, 0, L); partialSM<DQK, FIX>(pA0, pA1, m_reg, mnA, alA, mC); }
;   SLOAD(SO, KVBLK); if (2 < NT) SLOAD(SE, 2 * KVBLK);
;   SWAIT(); SWRITE(1, SO); __syncthreads();
.LBB0_879:
	s_or_b64 exec, exec, s[6:7]
	s_waitcnt vmcnt(2)
	s_waitcnt vmcnt(3)
	ds_write_b128 v193, v[2:5] offset:16384
	s_waitcnt vmcnt(2)
	ds_write_b128 v194, v[6:9] offset:49152
	s_and_saveexec_b64 s[2:3], s[8:9]
	ds_write_b128 v195, v[140:143] offset:49152
	s_or_b64 exec, exec, s[2:3]
	v_lshlrev_b32_e32 v3, 4, v192
	v_lshlrev_b32_e32 v2, 3, v192
	v_and_b32_e32 v3, 0xc0, v3
	v_lshlrev_b32_e32 v4, 1, v192
	v_and_or_b32 v3, v2, 24, v3
	v_and_b32_e32 v4, 32, v4
	v_and_b32_e32 v2, 0x100, v2
	s_cmp_lg_u32 0, -1
	v_or3_b32 v2, v3, v4, v2
	s_cselect_b32 s2, 0, 0
	v_add_u32_e32 v197, s2, v2
	s_addk_i32 s2, 0x4000
	s_lshr_b32 s16, s19, 1
	v_and_b32_e32 v3, 0x70, v31
	v_or_b32_e32 v4, 32, v0
	v_add_u32_e32 v199, s2, v2
	s_mul_i32 s2, s16, 0xc0
	s_mul_i32 s3, s18, 0x60
	v_xad_u32 v17, v4, v3, 0
	v_or_b32_e32 v4, 64, v0
	s_add_i32 s2, s2, s3
	v_xad_u32 v24, v4, v3, 0
	v_or_b32_e32 v4, 0x60, v0
	s_ashr_i32 s3, s2, 31
	v_xad_u32 v16, v0, v3, 0
	v_xad_u32 v25, v4, v3, 0
	v_or_b32_e32 v4, 0x80, v0
	v_or_b32_e32 v0, 0xa0, v0
	s_lshl_b64 s[6:7], s[2:3], 1
	s_mul_hi_u32 s2, s82, 0x600
	s_mul_i32 s3, s82, 0x600
	v_xad_u32 v26, v4, v3, 0
	v_xad_u32 v27, v0, v3, 0
	v_mov_b32_e32 v2, s3
	v_mov_b32_e32 v3, s2
	v_mad_i64_i32 v[2:3], s[2:3], v28, s65, v[2:3]
	v_readlane_b32 s20, v254, 35
	v_lshl_add_u64 v[2:3], v[22:23], 1, v[2:3]
	v_readlane_b32 s21, v254, 36
	s_sub_i32 s5, s96, 64
	s_sub_i32 s78, s96, 32
	v_lshl_add_u64 v[166:167], s[20:21], 0, v[2:3]
	v_mad_u64_u32 v[2:3], s[2:3], s82, v185, v[10:11]
	s_lshl_b32 s2, s16, 7
	s_lshl_b32 s3, s18, 6
	s_add_i32 s2, s2, s3
	v_lshl_add_u64 v[2:3], v[18:19], 1, v[2:3]
	s_ashr_i32 s3, s2, 31
	v_lshl_add_u64 v[168:169], s[20:21], 0, v[2:3]
	v_lshl_add_u64 v[2:3], v[20:21], 0, s[14:15]
	v_and_b32_e32 v0, 7, v176
	s_lshl_b64 s[2:3], s[2:3], 1
	v_readlane_b32 s14, v254, 57
	v_lshlrev_b32_e32 v0, 4, v0
	s_add_u32 s2, s14, s2
	v_readlane_b32 s14, v254, 58
	v_lshl_add_u64 v[2:3], v[2:3], 0, v[0:1]
	s_addc_u32 s3, s14, s3
	v_mov_b32_e32 v14, v1
	v_mov_b32_e32 v15, v1
	v_lshl_add_u64 v[170:171], s[2:3], 0, v[2:3]
	v_mov_b32_e32 v0, v1
	v_mov_b32_e32 v2, v1
	v_mov_b32_e32 v3, v1
	v_mov_b32_e32 v4, v1
	v_mov_b32_e32 v5, v1
	v_mov_b32_e32 v6, v1
	v_mov_b32_e32 v7, v1
	v_mov_b32_e32 v8, v1
	v_mov_b32_e32 v9, v1
	v_mov_b32_e32 v10, v1
	v_mov_b32_e32 v11, v1
	v_mov_b32_e32 v12, v1
	v_mov_b32_e32 v13, v1
	v_add_u32_e32 v200, v16, v29
	v_add_u32_e32 v201, v17, v29
	v_add_u32_e32 v202, v24, v29
	v_add_u32_e32 v203, v25, v29
	v_add_u32_e32 v204, v26, v29
	v_add_u32_e32 v205, v27, v29
	v_mov_b64_e32 v[46:47], v[14:15]
	v_mov_b64_e32 v[30:31], v[14:15]
	v_mov_b64_e32 v[94:95], v[14:15]
	v_mov_b64_e32 v[110:111], v[14:15]
	s_mov_b32 s79, 4
	s_mov_b32 s4, 0
	v_lshlrev_b32_e32 v196, 2, v189
	v_mov_b32_e32 v198, 0
	v_mov_b64_e32 v[44:45], v[12:13]
	v_mov_b64_e32 v[42:43], v[10:11]
	v_mov_b64_e32 v[40:41], v[8:9]
	v_mov_b64_e32 v[38:39], v[6:7]
	v_mov_b64_e32 v[36:37], v[4:5]
	v_mov_b64_e32 v[34:35], v[2:3]
	v_mov_b64_e32 v[32:33], v[0:1]
	v_mov_b64_e32 v[28:29], v[12:13]
	v_mov_b64_e32 v[26:27], v[10:11]
	v_mov_b64_e32 v[24:25], v[8:9]
	v_mov_b64_e32 v[22:23], v[6:7]
	v_mov_b64_e32 v[20:21], v[4:5]
	v_mov_b64_e32 v[18:19], v[2:3]
	v_mov_b64_e32 v[16:17], v[0:1]
	v_mov_b64_e32 v[92:93], v[12:13]
	v_mov_b64_e32 v[90:91], v[10:11]
	v_mov_b64_e32 v[88:89], v[8:9]
	v_mov_b64_e32 v[86:87], v[6:7]
	v_mov_b64_e32 v[84:85], v[4:5]
	v_mov_b64_e32 v[82:83], v[2:3]
	v_mov_b64_e32 v[80:81], v[0:1]
	v_mov_b64_e32 v[108:109], v[12:13]
	v_mov_b64_e32 v[106:107], v[10:11]
	v_mov_b64_e32 v[104:105], v[8:9]
	v_mov_b64_e32 v[102:103], v[6:7]
	v_mov_b64_e32 v[100:101], v[4:5]
	v_mov_b64_e32 v[98:99], v[2:3]
	v_mov_b64_e32 v[96:97], v[0:1]
	s_waitcnt lgkmcnt(0)
	s_barrier
	v_readlane_b32 s22, v254, 37
	v_readlane_b32 s23, v254, 38
	v_mov_b32_e32 v186, 0
	s_branch .LBB0_883

; #define SBAR() __builtin_amdgcn_sched_barrier(0)
; #define SLOAD(i, key0) do { sr_[i].v = *reinterpret_cast<const bf16x8*>(&Vh[(long)((key0) + vr) * ldv + vc]); \
;     sr_[i].k0 = *reinterpret_cast<const bf16x8*>(&Kh[(long)((key0) + kr0) * ldk + kc0]); \
;     if (k2) sr_[i].k1 = *reinterpret_cast<const bf16x8*>(&Kh[(long)((key0) + kr1) * ldk + kc1]); } while (0)
; template <int D0> __device__ __forceinline__ void pv_one(f32x16& od, int vb, bf16x8 pa0, bf16x8 pa1, bf16x8 pa2, bf16x8 pa3) {
;   const s16x4 l0 = tr_read<v_rd_off(D0, 0, 0)>(vb), h0 = tr_read<v_rd_off(D0, 0, 1)>(vb), l1 = tr_read<v_rd_off(D0, 1, 0)>(vb), h1 = tr_read<v_rd_off(D0, 1, 1)>(vb);
;   const s16x4 l2 = tr_read<v_rd_off(D0, 2, 0)>(vb), h2 = tr_read<v_rd_off(D0, 2, 1)>(vb), l3 = tr_read<v_rd_off(D0, 3, 0)>(vb), h3 = tr_read<v_rd_off(D0, 3, 1)>(vb);
;   asm volatile("s_waitcnt lgkmcnt(0)" ::: "memory"); SBAR();
;     ...
;   od = __builtin_amdgcn_mfma_f32_32x32x16_bf16(pa0, PK(l0, h0), od, 0, 0, 0);
;   od = __builtin_amdgcn_mfma_f32_32x32x16_bf16(pa1, PK(l1, h1), od, 0, 0, 0);
;   od = __builtin_amdgcn_mfma_f32_32x32x16_bf16(pa2, PK(l2, h2), od, 0, 0, 0);
;   od = __builtin_amdgcn_mfma_f32_32x32x16_bf16(pa3, PK(l3, h3), od, 0, 0, 0);
;     ...
; }
; __device__ __forceinline__ void pv_d0(f32x16* o, int vb, bf16x8 pa0, bf16x8 pa1, bf16x8 pa2, bf16x8 pa3) {
;   pv_one<0>(o[0], vb, pa0, pa1, pa2, pa3); pv_one<1>(o[1], vb, pa0, pa1, pa2, pa3);
; }
; template <int DQK, bool FIX>
; __device__ __forceinline__ void attn_item(const bf16* Qb, const bf16* __restrict__ Kh, const bf16* __restrict__ Vh,
;                                           u16* Ob, int q0, int L, int NT, char* lds, float mC) {
;     ...
;     if (act) { SBAR(); qkt<DQK>(pB0, pB1, (bf16*)((char*)K_lds + SHM_K), qr, r32, hi, j * KVBLK, L);
;       finishSM(pA0, pA1, alA, l_reg, pa0, pa1, pa2, pa3); SBAR(); }
;     SLOAD(SO, (j + 2) * KVBLK); SBAR();
;     if (act) { pv_d0(o, vb0, pa0, pa1, pa2, pa3); partialSM<DQK, FIX>(pB0, pB1, m_reg, mnB, alB, mC); }
.Lfast96a_k2:
	s_or_b64 exec, exec, s[2:3]
	s_and_saveexec_b64 s[2:3], s[10:11]
	v_mfma_f32_32x32x16_bf16 v[32:47], v[10:13], v[206:209], v[32:47]
	v_add_f32_e32 v0, v48, v0
	v_add_f32_e32 v0, v49, v0
	v_exp_f32_e32 v80, v80
	v_exp_f32_e32 v81, v81
	v_mfma_f32_32x32x16_bf16 v[32:47], v[152:155], v[210:213], v[32:47]
	v_add_f32_e32 v0, v50, v0
	v_add_f32_e32 v0, v51, v0
	v_exp_f32_e32 v82, v82
	v_exp_f32_e32 v83, v83
	v_mfma_f32_32x32x16_bf16 v[32:47], v[156:159], v[214:217], v[32:47]
	v_add_f32_e32 v0, v52, v0
	v_add_f32_e32 v0, v53, v0
	v_exp_f32_e32 v84, v84
	v_exp_f32_e32 v85, v85
	v_mfma_f32_32x32x16_bf16 v[32:47], v[160:163], v[218:221], v[32:47]
	v_add_f32_e32 v0, v54, v0
	v_add_f32_e32 v0, v55, v0
	v_exp_f32_e32 v86, v86
	v_exp_f32_e32 v87, v87
	s_waitcnt lgkmcnt(6)
	v_mfma_f32_32x32x16_bf16 v[16:31], v[10:13], v[238:241], v[16:31]
	v_add_f32_e32 v0, v56, v0
	v_add_f32_e32 v0, v57, v0
	v_exp_f32_e32 v88, v88
	v_exp_f32_e32 v89, v89
	s_waitcnt lgkmcnt(4)
	v_mfma_f32_32x32x16_bf16 v[16:31], v[152:155], v[242:245], v[16:31]
	v_add_f32_e32 v0, v58, v0
	v_add_f32_e32 v0, v59, v0
	v_exp_f32_e32 v90, v90
	v_exp_f32_e32 v91, v91
	s_waitcnt lgkmcnt(2)
	v_mfma_f32_32x32x16_bf16 v[16:31], v[156:159], v[246:249], v[16:31]
	v_add_f32_e32 v0, v60, v0
	v_add_f32_e32 v0, v61, v0
	v_exp_f32_e32 v92, v92
	v_exp_f32_e32 v93, v93
	s_waitcnt lgkmcnt(0)
	v_mfma_f32_32x32x16_bf16 v[16:31], v[160:163], v[250:253], v[16:31]
	v_add_f32_e32 v0, v62, v0
	v_add_f32_e32 v0, v63, v0
	v_exp_f32_e32 v94, v94
	v_exp_f32_e32 v95, v95
	v_add_f32_e32 v186, v186, v0
	s_branch .LBB0_895

; #define SBAR() __builtin_amdgcn_sched_barrier(0)
; #define SLOAD(i, key0) do { sr_[i].v = *reinterpret_cast<const bf16x8*>(&Vh[(long)((key0) + vr) * ldv + vc]); \
;     sr_[i].k0 = *reinterpret_cast<const bf16x8*>(&Kh[(long)((key0) + kr0) * ldk + kc0]); \
;     if (k2) sr_[i].k1 = *reinterpret_cast<const bf16x8*>(&Kh[(long)((key0) + kr1) * ldk + kc1]); } while (0)
; template <int D0> __device__ __forceinline__ void pv_one(f32x16& od, int vb, bf16x8 pa0, bf16x8 pa1, bf16x8 pa2, bf16x8 pa3) {
;   const s16x4 l0 = tr_read<v_rd_off(D0, 0, 0)>(vb), h0 = tr_read<v_rd_off(D0, 0, 1)>(vb), l1 = tr_read<v_rd_off(D0, 1, 0)>(vb), h1 = tr_read<v_rd_off(D0, 1, 1)>(vb);
;   const s16x4 l2 = tr_read<v_rd_off(D0, 2, 0)>(vb), h2 = tr_read<v_rd_off(D0, 2, 1)>(vb), l3 = tr_read<v_rd_off(D0, 3, 0)>(vb), h3 = tr_read<v_rd_off(D0, 3, 1)>(vb);
;   asm volatile("s_waitcnt lgkmcnt(0)" ::: "memory"); SBAR();
;     ...
;   od = __builtin_amdgcn_mfma_f32_32x32x16_bf16(pa0, PK(l0, h0), od, 0, 0, 0);
;   od = __builtin_amdgcn_mfma_f32_32x32x16_bf16(pa1, PK(l1, h1), od, 0, 0, 0);
;   od = __builtin_amdgcn_mfma_f32_32x32x16_bf16(pa2, PK(l2, h2), od, 0, 0, 0);
;   od = __builtin_amdgcn_mfma_f32_32x32x16_bf16(pa3, PK(l3, h3), od, 0, 0, 0);
;     ...
; }
; __device__ __forceinline__ void pv_d0(f32x16* o, int vb, bf16x8 pa0, bf16x8 pa1, bf16x8 pa2, bf16x8 pa3) {
;   pv_one<0>(o[0], vb, pa0, pa1, pa2, pa3); pv_one<1>(o[1], vb, pa0, pa1, pa2, pa3);
; }
; template <int DQK, bool FIX>
; __device__ __forceinline__ void attn_item(const bf16* Qb, const bf16* __restrict__ Kh, const bf16* __restrict__ Vh,
;                                           u16* Ob, int q0, int L, int NT, char* lds, float mC) {
;     ...
;     if (act) { SBAR(); qkt<DQK>(pA0, pA1, K_lds, qr, r32, hi, (j + 1) * KVBLK, L);
;       finishSM(pB0, pB1, alB, l_reg, pa0, pa1, pa2, pa3); SBAR(); }
;     if (j + 3 < NT) SLOAD(SE, (j + 3) * KVBLK); SBAR();
;     if (act) { pv_d0(o, vb0 + (int)SHM_V, pa0, pa1, pa2, pa3); partialSM<DQK, FIX>(pA0, pA1, m_reg, mnA, alA, mC); }
.Lfast96b_nl:
	s_and_saveexec_b64 s[14:15], s[10:11]
	v_mfma_f32_32x32x16_bf16 v[32:47], v[10:13], v[206:209], v[32:47]
	v_add_f32_e32 v0, v96, v0
	v_add_f32_e32 v0, v97, v0
	v_exp_f32_e32 v64, v64
	v_exp_f32_e32 v65, v65
	v_mfma_f32_32x32x16_bf16 v[32:47], v[152:155], v[210:213], v[32:47]
	v_add_f32_e32 v0, v98, v0
	v_add_f32_e32 v0, v99, v0
	v_exp_f32_e32 v66, v66
	v_exp_f32_e32 v67, v67
	v_mfma_f32_32x32x16_bf16 v[32:47], v[156:159], v[214:217], v[32:47]
	v_add_f32_e32 v0, v100, v0
	v_add_f32_e32 v0, v101, v0
	v_exp_f32_e32 v68, v68
	v_exp_f32_e32 v69, v69
	v_mfma_f32_32x32x16_bf16 v[32:47], v[160:163], v[218:221], v[32:47]
	v_add_f32_e32 v0, v102, v0
	v_add_f32_e32 v0, v103, v0
	v_exp_f32_e32 v70, v70
	v_exp_f32_e32 v71, v71
	s_waitcnt lgkmcnt(6)
	v_mfma_f32_32x32x16_bf16 v[16:31], v[10:13], v[238:241], v[16:31]
	v_add_f32_e32 v0, v104, v0
	v_add_f32_e32 v0, v105, v0
	v_exp_f32_e32 v72, v72
	v_exp_f32_e32 v73, v73
	s_waitcnt lgkmcnt(4)
	v_mfma_f32_32x32x16_bf16 v[16:31], v[152:155], v[242:245], v[16:31]
	v_add_f32_e32 v0, v106, v0
	v_add_f32_e32 v0, v107, v0
	v_exp_f32_e32 v74, v74
	v_exp_f32_e32 v75, v75
	s_waitcnt lgkmcnt(2)
	v_mfma_f32_32x32x16_bf16 v[16:31], v[156:159], v[246:249], v[16:31]
	v_add_f32_e32 v0, v108, v0
	v_add_f32_e32 v0, v109, v0
	v_exp_f32_e32 v76, v76
	v_exp_f32_e32 v77, v77
	s_waitcnt lgkmcnt(0)
	v_mfma_f32_32x32x16_bf16 v[16:31], v[160:163], v[250:253], v[16:31]
	v_add_f32_e32 v0, v110, v0
	v_add_f32_e32 v0, v111, v0
	v_exp_f32_e32 v78, v78
	v_exp_f32_e32 v79, v79
	v_add_f32_e32 v186, v186, v0
	s_branch .LBB0_911

; __device__ __forceinline__ void finishSM(f32x16& p0, f32x16& p1, float alpha, float& l_reg, bf16x8& pa0, bf16x8& pa1, bf16x8& pa2, bf16x8& pa3) {
; #pragma unroll
;   for (int r = 0; r < 16; ++r) p1[r] = __builtin_amdgcn_exp2f(p1[r]);
;   float ps = 0;
; #pragma unroll
;   for (int r = 0; r < 16; ++r) ps += p0[r];
; #pragma unroll
;   for (int r = 0; r < 16; ++r) ps += p1[r];
;   { auto rr = __builtin_amdgcn_permlane32_swap(__float_as_uint(ps), __float_as_uint(ps), false, false);
;     ps = __uint_as_float(rr[0]) + __uint_as_float(rr[1]); }
;   l_reg = l_reg * alpha + ps;
;     ...
;   PK4(p0, 0, pa0); PK4(p0, 8, pa1); PK4(p1, 0, pa2); PK4(p1, 8, pa3);
;     ...
; }
; template <int DQK>
; __device__ __forceinline__ void qkt(f32x16& p0, f32x16& p1, const bf16* Ks, const bf16x8* qr, int r32, int hi, int k0, int L) {
;   p0 = f32x16{}; p1 = f32x16{};
; #pragma unroll
;   for (int d0 = 0; d0 < DQK / 16; ++d0) { int cb = (d0 * 16 + hi * 8) * 2;
;     bf16x8 b0 = *reinterpret_cast<const bf16x8*>((const char*)Ks + KSWZ(r32, cb));
;     bf16x8 b1 = *reinterpret_cast<const bf16x8*>((const char*)Ks + KSWZ(32 + r32, cb));
;     p0 = __builtin_amdgcn_mfma_f32_32x32x16_bf16(b0, qr[d0], p0, 0, 0, 0);
;     p1 = __builtin_amdgcn_mfma_f32_32x32x16_bf16(b1, qr[d0], p1, 0, 0, 0); }
;   if (k0 + KVBLK > L) {
; #pragma unroll
;     for (int r = 0; r < 16; ++r) { const int key = k0 + crow(r, hi);
;       if (key >= L) p0[r] = -1e30f;
;       if (key + 32 >= L) p1[r] = -1e30f; }
;   }
; }
; __device__ __forceinline__ int v_st(int k, int c) { const int kk = (k & ~0xC) | ((k & 4) << 1) | ((k & 8) >> 1); return ((kk >> 3) * 4 + (c >> 5)) * 512 + ((kk & 7) * 32 + (c & 31)) * 2; }
; __device__ __forceinline__ int v_rd_base(int lane) { return ((lane & 3) << 3) | (((lane >> 2) & 3) << 6) | (((lane >> 4) & 1) << 5) | (((lane >> 5) & 1) << 8); }
; template <int OFF> __device__ __forceinline__ s16x4 tr_read(int vb) {
;   s16x4 r; asm volatile("ds_read_b64_tr_b16 %0, %1 offset:%2" : "=&v"(r) : "v"(vb), "i"(OFF) : "memory"); return r;
; }
; template <int D0> __device__ __forceinline__ void pv_one(f32x16& od, int vb, bf16x8 pa0, bf16x8 pa1, bf16x8 pa2, bf16x8 pa3) {
;   const s16x4 l0 = tr_read<v_rd_off(D0, 0, 0)>(vb), h0 = tr_read<v_rd_off(D0, 0, 1)>(vb), l1 = tr_read<v_rd_off(D0, 1, 0)>(vb), h1 = tr_read<v_rd_off(D0, 1, 1)>(vb);
.LBB0_913:
	s_and_saveexec_b64 s[2:3], s[10:11]
	s_cbranch_execz .LBB0_915
	v_mov_b32_e32 v187, v186
	s_nop 1
	v_permlane32_swap_b32_e32 v186, v187
	v_add_f32_e32 v186, v186, v187
	v_add_f32_e32 v198, v198, v186
	v_add_f32_e32 v2, 0, v64
	v_add_f32_e32 v2, v65, v2
	v_add_f32_e32 v2, v66, v2
	v_add_f32_e32 v2, v67, v2
	v_add_f32_e32 v2, v68, v2
	v_add_f32_e32 v2, v69, v2
	v_add_f32_e32 v2, v70, v2
	v_add_f32_e32 v2, v71, v2
	v_add_f32_e32 v2, v72, v2
	v_add_f32_e32 v2, v73, v2
	v_add_f32_e32 v2, v74, v2
	v_add_f32_e32 v2, v75, v2
	v_exp_f32_e32 v0, v48
	v_add_f32_e32 v2, v76, v2
	v_exp_f32_e32 v10, v49
	v_add_f32_e32 v2, v77, v2
	v_exp_f32_e32 v11, v50
	v_add_f32_e32 v2, v78, v2
	v_exp_f32_e32 v12, v51
	v_add_f32_e32 v2, v79, v2
	v_exp_f32_e32 v13, v52
	v_add_f32_e32 v2, v0, v2
	v_exp_f32_e32 v14, v53
	v_add_f32_e32 v2, v10, v2
	v_exp_f32_e32 v15, v54
	v_add_f32_e32 v2, v11, v2
	v_exp_f32_e32 v48, v55
	v_add_f32_e32 v2, v12, v2
	v_exp_f32_e32 v49, v56
	v_add_f32_e32 v2, v13, v2
	v_exp_f32_e32 v50, v57
	v_add_f32_e32 v2, v14, v2
	v_exp_f32_e32 v51, v58
	v_add_f32_e32 v2, v15, v2
	v_exp_f32_e32 v52, v59
	v_add_f32_e32 v2, v48, v2
	v_exp_f32_e32 v53, v60
	v_add_f32_e32 v2, v49, v2
	v_exp_f32_e32 v54, v61
	v_add_f32_e32 v2, v50, v2
	v_exp_f32_e32 v55, v62
	v_add_f32_e32 v2, v51, v2
	v_exp_f32_e32 v56, v63
	v_add_f32_e32 v2, v52, v2
	v_add_f32_e32 v2, v53, v2
	v_add_f32_e32 v2, v54, v2
	v_add_f32_e32 v2, v55, v2
	v_add_f32_e32 v2, v56, v2
	v_mov_b32_e32 v3, v2
	s_nop 1
	v_permlane32_swap_b32_e32 v2, v3
	v_add_f32_e32 v2, v2, v3
	v_add_f32_e32 v198, v198, v2
	v_cvt_pk_bf16_f32 v2, v64, v65
	v_cvt_pk_bf16_f32 v3, v66, v67
	v_cvt_pk_bf16_f32 v4, v68, v69
	v_cvt_pk_bf16_f32 v5, v70, v71
	v_cvt_pk_bf16_f32 v6, v72, v73
	v_cvt_pk_bf16_f32 v7, v74, v75
	v_cvt_pk_bf16_f32 v8, v76, v77
	v_cvt_pk_bf16_f32 v9, v78, v79
	v_cvt_pk_bf16_f32 v10, v0, v10
	v_cvt_pk_bf16_f32 v11, v11, v12
	v_cvt_pk_bf16_f32 v12, v13, v14
	v_cvt_pk_bf16_f32 v13, v15, v48
	v_cvt_pk_bf16_f32 v48, v49, v50
	v_cvt_pk_bf16_f32 v49, v51, v52
	v_cvt_pk_bf16_f32 v50, v53, v54
	v_cvt_pk_bf16_f32 v51, v55, v56
	ds_read_b64_tr_b16 v[52:53], v197 offset:0
	ds_read_b64_tr_b16 v[54:55], v197 offset:0x800
	ds_read_b64_tr_b16 v[56:57], v197 offset:0x1000
	ds_read_b64_tr_b16 v[58:59], v197 offset:0x1800
	ds_read_b64_tr_b16 v[60:61], v197 offset:0x2000
	ds_read_b64_tr_b16 v[62:63], v197 offset:0x2800
	ds_read_b64_tr_b16 v[64:65], v197 offset:0x3000
	ds_read_b64_tr_b16 v[66:67], v197 offset:0x3800
	s_waitcnt lgkmcnt(0)
	s_nop 0
	v_mfma_f32_32x32x16_bf16 v[32:47], v[2:5], v[52:55], v[32:47]
	ds_read_b64_tr_b16 v[52:53], v197 offset:0x200
	ds_read_b64_tr_b16 v[54:55], v197 offset:0xa00
	v_mfma_f32_32x32x16_bf16 v[32:47], v[6:9], v[56:59], v[32:47]
	ds_read_b64_tr_b16 v[56:57], v197 offset:0x1200
	ds_read_b64_tr_b16 v[58:59], v197 offset:0x1a00
	v_mfma_f32_32x32x16_bf16 v[32:47], v[10:13], v[60:63], v[32:47]
	ds_read_b64_tr_b16 v[60:61], v197 offset:0x2200
	ds_read_b64_tr_b16 v[62:63], v197 offset:0x2a00
	v_mfma_f32_32x32x16_bf16 v[32:47], v[48:51], v[64:67], v[32:47]
	ds_read_b64_tr_b16 v[64:65], v197 offset:0x3200
	ds_read_b64_tr_b16 v[66:67], v197 offset:0x3a00
	s_waitcnt lgkmcnt(0)
	v_mfma_f32_32x32x16_bf16 v[16:31], v[2:5], v[52:55], v[16:31]
	v_mfma_f32_32x32x16_bf16 v[16:31], v[6:9], v[56:59], v[16:31]
	v_mfma_f32_32x32x16_bf16 v[16:31], v[10:13], v[60:63], v[16:31]
	v_mfma_f32_32x32x16_bf16 v[16:31], v[48:51], v[64:67], v[16:31]
